# prologue row->bf16+sum-of-squares conversion: 8 loads in flight per wave instead of one load/wait/store at a time (on top of best)
# speedup vs baseline: 1.0063x; 1.0063x over previous
; __device__ __forceinline__ unsigned cvt_pk_bf16(float lo, float hi) { unsigned r; asm volatile("v_cvt_pk_bf16_f32 %0, %1, %2" : "=v"(r) : "v"(lo), "v"(hi)); return r; }
; __device__ __forceinline__ void row_to_bf16_ss(const float* xrow, bf16_t* orow, float* ssp, int lane) {
;     const f32x4* xr = (const f32x4*)xrow + lane; u32x2* o8 = (u32x2*)orow + lane; float s = 0.f;
; #pragma unroll
;     for (int j = 0; j < 16; ++j) { const f32x4 v = xr[64 * j]; s += (v[0] * v[0] + v[1] * v[1]) + (v[2] * v[2] + v[3] * v[3]);
;         u32x2 w; w.x = cvt_pk_bf16(v[0], v[1]); w.y = cvt_pk_bf16(v[2], v[3]); o8[64 * j] = w; }
; __device__ __forceinline__ void p0_prologue(const Args& a, LAS unsigned char* lds, int vcu, int G, int tid, int wave, int lane) {
;     ...
;         else row_to_bf16_ss(a.in[I_MEMP] + (size_t)(m - M) * DM, (bf16_t*)(ws + WS_MEMB) + (size_t)(m - M) * DM, ssm + (m - M), lane);
.LBB0_43:
	s_cmpk_gt_i32 s26, 0x1fff
	s_mov_b64 s[4:5], -1
	s_cbranch_scc0 .LBB0_53
	s_mov_b64 s[14:15], -1
	s_cmpk_gt_u32 s26, 0x21ff
	v_cmp_lt_i32_e64 s[12:13], v42, v41
	v_cmp_lt_i32_e64 s[10:11], v43, v41
	v_cmp_lt_i32_e64 s[8:9], v44, v41
	v_cmp_lt_i32_e64 s[6:7], v45, v41
	v_cmp_lt_i32_e64 s[4:5], v46, v41
	v_cmp_lt_i32_e32 vcc, v47, v41
	s_cbranch_scc0 .LBB0_48
	s_add_i32 s34, s26, 0xffffde00
	s_mov_b32 s35, s27
	s_lshl_b64 s[14:15], s[34:35], 14
	s_waitcnt lgkmcnt(0)
	v_lshl_add_u64 v[76:77], v[30:31], 0, s[14:15]
	s_lshl_b64 s[14:15], s[34:35], 13
	v_lshl_add_u64 v[78:79], v[26:27], 0, s[14:15]
	s_mov_b64 s[14:15], 0x2000
	v_lshl_add_u64 v[70:71], v[76:77], 0, s[14:15]
	v_lshl_add_u64 v[72:73], v[70:71], 0, s[14:15]
	s_mov_b64 s[14:15], 0x1000
	v_lshl_add_u64 v[74:75], v[78:79], 0, s[14:15]
	v_mov_b32_e32 v62, 0
	global_load_dwordx4 v[2:5], v[76:77], off nt
	global_load_dwordx4 v[6:9], v[76:77], off offset:1024 nt
	global_load_dwordx4 v[10:13], v[76:77], off offset:2048 nt
	global_load_dwordx4 v[14:17], v[76:77], off offset:3072 nt
	global_load_dwordx4 v[18:21], v[70:71], off offset:-4096 nt
	global_load_dwordx4 v[22:25], v[70:71], off offset:-3072 nt
	global_load_dwordx4 v[48:51], v[70:71], off offset:-2048 nt
	global_load_dwordx4 v[52:55], v[70:71], off offset:-1024 nt
	s_waitcnt vmcnt(7)
	v_mul_f32_e32 v60, v3, v3
	v_mul_f32_e32 v61, v5, v5
	v_fmac_f32_e32 v60, v2, v2
	v_fmac_f32_e32 v61, v4, v4
	v_cvt_pk_bf16_f32 v56, v2, v3
	v_cvt_pk_bf16_f32 v57, v4, v5
	v_add_f32_e32 v60, v60, v61
	global_store_dwordx2 v[78:79], v[56:57], off
	v_add_f32_e32 v62, v62, v60
	global_load_dwordx4 v[2:5], v[70:71], off nt
	s_waitcnt vmcnt(8)
	v_mul_f32_e32 v60, v7, v7
	v_mul_f32_e32 v61, v9, v9
	v_fmac_f32_e32 v60, v6, v6
	v_fmac_f32_e32 v61, v8, v8
	v_cvt_pk_bf16_f32 v58, v6, v7
	v_cvt_pk_bf16_f32 v59, v8, v9
	v_add_f32_e32 v60, v60, v61
	global_store_dwordx2 v[78:79], v[58:59], off offset:512
	v_add_f32_e32 v62, v62, v60
	global_load_dwordx4 v[6:9], v[70:71], off offset:1024 nt
	s_waitcnt vmcnt(9)
	v_mul_f32_e32 v60, v11, v11
	v_mul_f32_e32 v61, v13, v13
	v_fmac_f32_e32 v60, v10, v10
	v_fmac_f32_e32 v61, v12, v12
	v_cvt_pk_bf16_f32 v56, v10, v11
	v_cvt_pk_bf16_f32 v57, v12, v13
	v_add_f32_e32 v60, v60, v61
	global_store_dwordx2 v[78:79], v[56:57], off offset:1024
	v_add_f32_e32 v62, v62, v60
	global_load_dwordx4 v[10:13], v[70:71], off offset:2048 nt
	s_waitcnt vmcnt(10)
	v_mul_f32_e32 v60, v15, v15
	v_mul_f32_e32 v61, v17, v17
	v_fmac_f32_e32 v60, v14, v14
	v_fmac_f32_e32 v61, v16, v16
	v_cvt_pk_bf16_f32 v58, v14, v15
	v_cvt_pk_bf16_f32 v59, v16, v17
	v_add_f32_e32 v60, v60, v61
	global_store_dwordx2 v[78:79], v[58:59], off offset:1536
	v_add_f32_e32 v62, v62, v60
	global_load_dwordx4 v[14:17], v[70:71], off offset:3072 nt
	s_waitcnt vmcnt(11)
	v_mul_f32_e32 v60, v19, v19
	v_mul_f32_e32 v61, v21, v21
	v_fmac_f32_e32 v60, v18, v18
	v_fmac_f32_e32 v61, v20, v20
	v_cvt_pk_bf16_f32 v56, v18, v19
	v_cvt_pk_bf16_f32 v57, v20, v21
	v_add_f32_e32 v60, v60, v61
	global_store_dwordx2 v[78:79], v[56:57], off offset:2048
	v_add_f32_e32 v62, v62, v60
	global_load_dwordx4 v[18:21], v[72:73], off offset:-4096 nt
	s_waitcnt vmcnt(12)
	v_mul_f32_e32 v60, v23, v23
	v_mul_f32_e32 v61, v25, v25
	v_fmac_f32_e32 v60, v22, v22
	v_fmac_f32_e32 v61, v24, v24
	v_cvt_pk_bf16_f32 v58, v22, v23
	v_cvt_pk_bf16_f32 v59, v24, v25
	v_add_f32_e32 v60, v60, v61
	global_store_dwordx2 v[78:79], v[58:59], off offset:2560
	v_add_f32_e32 v62, v62, v60
	global_load_dwordx4 v[22:25], v[72:73], off offset:-3072 nt
	s_waitcnt vmcnt(13)
	v_mul_f32_e32 v60, v49, v49
	v_mul_f32_e32 v61, v51, v51
	v_fmac_f32_e32 v60, v48, v48
	v_fmac_f32_e32 v61, v50, v50
	v_cvt_pk_bf16_f32 v56, v48, v49
	v_cvt_pk_bf16_f32 v57, v50, v51
	v_add_f32_e32 v60, v60, v61
	global_store_dwordx2 v[78:79], v[56:57], off offset:3072
	v_add_f32_e32 v62, v62, v60
	global_load_dwordx4 v[48:51], v[72:73], off offset:-2048 nt
	s_waitcnt vmcnt(14)
; __device__ __forceinline__ unsigned cvt_pk_bf16(float lo, float hi) { unsigned r; asm volatile("v_cvt_pk_bf16_f32 %0, %1, %2" : "=v"(r) : "v"(lo), "v"(hi)); return r; }
; __device__ __forceinline__ void row_to_bf16_ss(const float* xrow, bf16_t* orow, float* ssp, int lane) {
;     ...
;     for (int j = 0; j < 16; ++j) { const f32x4 v = xr[64 * j]; s += (v[0] * v[0] + v[1] * v[1]) + (v[2] * v[2] + v[3] * v[3]);
;         u32x2 w; w.x = cvt_pk_bf16(v[0], v[1]); w.y = cvt_pk_bf16(v[2], v[3]); o8[64 * j] = w; }
;     s = wave_sum(s); if (lane == 0) *ssp = s;
; }
	v_mul_f32_e32 v60, v53, v53
	v_mul_f32_e32 v61, v55, v55
	v_fmac_f32_e32 v60, v52, v52
	v_fmac_f32_e32 v61, v54, v54
	v_cvt_pk_bf16_f32 v58, v52, v53
	v_cvt_pk_bf16_f32 v59, v54, v55
	v_add_f32_e32 v60, v60, v61
	global_store_dwordx2 v[78:79], v[58:59], off offset:3584
	v_add_f32_e32 v62, v62, v60
	global_load_dwordx4 v[52:55], v[72:73], off offset:-1024 nt
	s_waitcnt vmcnt(14)
	v_mul_f32_e32 v60, v3, v3
	v_mul_f32_e32 v61, v5, v5
	v_fmac_f32_e32 v60, v2, v2
	v_fmac_f32_e32 v61, v4, v4
	v_cvt_pk_bf16_f32 v56, v2, v3
	v_cvt_pk_bf16_f32 v57, v4, v5
	v_add_f32_e32 v60, v60, v61
	global_store_dwordx2 v[74:75], v[56:57], off
	v_add_f32_e32 v62, v62, v60
	s_waitcnt vmcnt(13)
	v_mul_f32_e32 v60, v7, v7
	v_mul_f32_e32 v61, v9, v9
	v_fmac_f32_e32 v60, v6, v6
	v_fmac_f32_e32 v61, v8, v8
	v_cvt_pk_bf16_f32 v58, v6, v7
	v_cvt_pk_bf16_f32 v59, v8, v9
	v_add_f32_e32 v60, v60, v61
	global_store_dwordx2 v[74:75], v[58:59], off offset:512
	v_add_f32_e32 v62, v62, v60
	s_waitcnt vmcnt(12)
	v_mul_f32_e32 v60, v11, v11
	v_mul_f32_e32 v61, v13, v13
	v_fmac_f32_e32 v60, v10, v10
	v_fmac_f32_e32 v61, v12, v12
	v_cvt_pk_bf16_f32 v56, v10, v11
	v_cvt_pk_bf16_f32 v57, v12, v13
	v_add_f32_e32 v60, v60, v61
	global_store_dwordx2 v[74:75], v[56:57], off offset:1024
	v_add_f32_e32 v62, v62, v60
	s_waitcnt vmcnt(11)
	v_mul_f32_e32 v60, v15, v15
	v_mul_f32_e32 v61, v17, v17
	v_fmac_f32_e32 v60, v14, v14
	v_fmac_f32_e32 v61, v16, v16
	v_cvt_pk_bf16_f32 v58, v14, v15
	v_cvt_pk_bf16_f32 v59, v16, v17
	v_add_f32_e32 v60, v60, v61
	global_store_dwordx2 v[74:75], v[58:59], off offset:1536
	v_add_f32_e32 v62, v62, v60
	s_waitcnt vmcnt(10)
	v_mul_f32_e32 v60, v19, v19
	v_mul_f32_e32 v61, v21, v21
	v_fmac_f32_e32 v60, v18, v18
	v_fmac_f32_e32 v61, v20, v20
	v_cvt_pk_bf16_f32 v56, v18, v19
	v_cvt_pk_bf16_f32 v57, v20, v21
	v_add_f32_e32 v60, v60, v61
	global_store_dwordx2 v[74:75], v[56:57], off offset:2048
	v_add_f32_e32 v62, v62, v60
	s_waitcnt vmcnt(9)
	v_mul_f32_e32 v60, v23, v23
	v_mul_f32_e32 v61, v25, v25
	v_fmac_f32_e32 v60, v22, v22
	v_fmac_f32_e32 v61, v24, v24
	v_cvt_pk_bf16_f32 v58, v22, v23
	v_cvt_pk_bf16_f32 v59, v24, v25
	v_add_f32_e32 v60, v60, v61
	global_store_dwordx2 v[74:75], v[58:59], off offset:2560
	v_add_f32_e32 v62, v62, v60
	s_waitcnt vmcnt(8)
	v_mul_f32_e32 v60, v49, v49
	v_mul_f32_e32 v61, v51, v51
	v_fmac_f32_e32 v60, v48, v48
	v_fmac_f32_e32 v61, v50, v50
	v_cvt_pk_bf16_f32 v56, v48, v49
	v_cvt_pk_bf16_f32 v57, v50, v51
	v_add_f32_e32 v60, v60, v61
	global_store_dwordx2 v[74:75], v[56:57], off offset:3072
	v_add_f32_e32 v62, v62, v60
	s_waitcnt vmcnt(7)
	v_mul_f32_e32 v60, v53, v53
	v_mul_f32_e32 v61, v55, v55
	v_fmac_f32_e32 v60, v52, v52
	v_fmac_f32_e32 v61, v54, v54
	v_cvt_pk_bf16_f32 v58, v52, v53
	v_cvt_pk_bf16_f32 v59, v54, v55
	v_add_f32_e32 v60, v60, v61
	global_store_dwordx2 v[74:75], v[58:59], off offset:3584
	v_add_f32_e32 v62, v62, v60
	v_mov_b32_e32 v10, v62
	v_cndmask_b32_e64 v2, v40, v42, s[12:13]
	v_lshlrev_b32_e32 v2, 2, v2
	ds_bpermute_b32 v2, v2, v10
	v_cndmask_b32_e64 v3, v40, v43, s[10:11]
	v_lshlrev_b32_e32 v3, 2, v3
	s_waitcnt lgkmcnt(0)
	v_add_f32_e32 v2, v10, v2
	ds_bpermute_b32 v3, v3, v2
	s_waitcnt lgkmcnt(0)
	v_add_f32_e32 v2, v2, v3
	v_cndmask_b32_e64 v3, v40, v44, s[8:9]
	v_lshlrev_b32_e32 v3, 2, v3
	ds_bpermute_b32 v3, v3, v2
	s_waitcnt lgkmcnt(0)
	v_add_f32_e32 v2, v2, v3
	v_cndmask_b32_e64 v3, v40, v45, s[6:7]
	v_lshlrev_b32_e32 v3, 2, v3
	ds_bpermute_b32 v3, v3, v2
	s_waitcnt lgkmcnt(0)
	v_add_f32_e32 v2, v2, v3
	v_cndmask_b32_e64 v3, v40, v46, s[4:5]
	v_lshlrev_b32_e32 v3, 2, v3
	ds_bpermute_b32 v3, v3, v2
	s_waitcnt lgkmcnt(0)
	v_add_f32_e32 v2, v2, v3
	v_cndmask_b32_e32 v3, v40, v47, vcc
	v_lshlrev_b32_e32 v3, 2, v3
	ds_bpermute_b32 v3, v3, v2
	s_and_saveexec_b64 s[4:5], s[0:1]
	s_cbranch_execz .LBB0_47
	s_lshl_b64 s[6:7], s[34:35], 2
	s_add_u32 s6, s30, s6
	s_addc_u32 s7, s31, s7
	s_waitcnt lgkmcnt(0)
	v_add_f32_e32 v2, v2, v3
	global_store_dword v67, v2, s[6:7]

; __device__ __forceinline__ unsigned cvt_pk_bf16(float lo, float hi) { unsigned r; asm volatile("v_cvt_pk_bf16_f32 %0, %1, %2" : "=v"(r) : "v"(lo), "v"(hi)); return r; }
; __device__ __forceinline__ void row_to_bf16_ss(const float* xrow, bf16_t* orow, float* ssp, int lane) {
;     const f32x4* xr = (const f32x4*)xrow + lane; u32x2* o8 = (u32x2*)orow + lane; float s = 0.f;
; #pragma unroll
;     for (int j = 0; j < 16; ++j) { const f32x4 v = xr[64 * j]; s += (v[0] * v[0] + v[1] * v[1]) + (v[2] * v[2] + v[3] * v[3]);
;         u32x2 w; w.x = cvt_pk_bf16(v[0], v[1]); w.y = cvt_pk_bf16(v[2], v[3]); o8[64 * j] = w; }
; __device__ __forceinline__ void p0_prologue(const Args& a, LAS unsigned char* lds, int vcu, int G, int tid, int wave, int lane) {
;     ...
;         else if (m < M) row_to_bf16_ss(a.in[I_XS] + (size_t)(m - MP) * DM, (bf16_t*)(ws + WS_XB) + (size_t)m * DM, ss0 + m, lane);
.LBB0_48:
	s_andn2_b64 vcc, exec, s[14:15]
	s_cbranch_vccnz .LBB0_52
	s_add_i32 s4, s26, 0xffffe000
	s_mov_b32 s5, s27
	s_lshl_b64 s[4:5], s[4:5], 14
	v_lshl_add_u64 v[76:77], v[32:33], 0, s[4:5]
	s_lshl_b64 s[4:5], s[26:27], 13
	s_waitcnt lgkmcnt(0)
	v_lshl_add_u64 v[78:79], v[28:29], 0, s[4:5]
	s_mov_b64 s[4:5], 0x2000
	v_lshl_add_u64 v[70:71], v[76:77], 0, s[4:5]
	v_lshl_add_u64 v[72:73], v[70:71], 0, s[4:5]
	s_mov_b64 s[4:5], 0x1000
	v_lshl_add_u64 v[74:75], v[78:79], 0, s[4:5]
	v_mov_b32_e32 v62, 0
	global_load_dwordx4 v[2:5], v[76:77], off nt
	global_load_dwordx4 v[6:9], v[76:77], off offset:1024 nt
	global_load_dwordx4 v[10:13], v[76:77], off offset:2048 nt
	global_load_dwordx4 v[14:17], v[76:77], off offset:3072 nt
	global_load_dwordx4 v[18:21], v[70:71], off offset:-4096 nt
	global_load_dwordx4 v[22:25], v[70:71], off offset:-3072 nt
	global_load_dwordx4 v[48:51], v[70:71], off offset:-2048 nt
	global_load_dwordx4 v[52:55], v[70:71], off offset:-1024 nt
	s_waitcnt vmcnt(7)
	v_mul_f32_e32 v60, v3, v3
	v_mul_f32_e32 v61, v5, v5
	v_fmac_f32_e32 v60, v2, v2
	v_fmac_f32_e32 v61, v4, v4
	v_cvt_pk_bf16_f32 v56, v2, v3
	v_cvt_pk_bf16_f32 v57, v4, v5
	v_add_f32_e32 v60, v60, v61
	global_store_dwordx2 v[78:79], v[56:57], off
	v_add_f32_e32 v62, v62, v60
	global_load_dwordx4 v[2:5], v[70:71], off nt
	s_waitcnt vmcnt(8)
	v_mul_f32_e32 v60, v7, v7
	v_mul_f32_e32 v61, v9, v9
	v_fmac_f32_e32 v60, v6, v6
	v_fmac_f32_e32 v61, v8, v8
	v_cvt_pk_bf16_f32 v58, v6, v7
	v_cvt_pk_bf16_f32 v59, v8, v9
	v_add_f32_e32 v60, v60, v61
	global_store_dwordx2 v[78:79], v[58:59], off offset:512
	v_add_f32_e32 v62, v62, v60
	global_load_dwordx4 v[6:9], v[70:71], off offset:1024 nt
	s_waitcnt vmcnt(9)
	v_mul_f32_e32 v60, v11, v11
	v_mul_f32_e32 v61, v13, v13
	v_fmac_f32_e32 v60, v10, v10
	v_fmac_f32_e32 v61, v12, v12
	v_cvt_pk_bf16_f32 v56, v10, v11
	v_cvt_pk_bf16_f32 v57, v12, v13
	v_add_f32_e32 v60, v60, v61
	global_store_dwordx2 v[78:79], v[56:57], off offset:1024
	v_add_f32_e32 v62, v62, v60
	global_load_dwordx4 v[10:13], v[70:71], off offset:2048 nt
	s_waitcnt vmcnt(10)
	v_mul_f32_e32 v60, v15, v15
	v_mul_f32_e32 v61, v17, v17
	v_fmac_f32_e32 v60, v14, v14
	v_fmac_f32_e32 v61, v16, v16
	v_cvt_pk_bf16_f32 v58, v14, v15
	v_cvt_pk_bf16_f32 v59, v16, v17
	v_add_f32_e32 v60, v60, v61
	global_store_dwordx2 v[78:79], v[58:59], off offset:1536
	v_add_f32_e32 v62, v62, v60
	global_load_dwordx4 v[14:17], v[70:71], off offset:3072 nt
	s_waitcnt vmcnt(11)
	v_mul_f32_e32 v60, v19, v19
	v_mul_f32_e32 v61, v21, v21
	v_fmac_f32_e32 v60, v18, v18
	v_fmac_f32_e32 v61, v20, v20
	v_cvt_pk_bf16_f32 v56, v18, v19
	v_cvt_pk_bf16_f32 v57, v20, v21
	v_add_f32_e32 v60, v60, v61
	global_store_dwordx2 v[78:79], v[56:57], off offset:2048
	v_add_f32_e32 v62, v62, v60
	global_load_dwordx4 v[18:21], v[72:73], off offset:-4096 nt
	s_waitcnt vmcnt(12)
	v_mul_f32_e32 v60, v23, v23
	v_mul_f32_e32 v61, v25, v25
	v_fmac_f32_e32 v60, v22, v22
	v_fmac_f32_e32 v61, v24, v24
	v_cvt_pk_bf16_f32 v58, v22, v23
	v_cvt_pk_bf16_f32 v59, v24, v25
	v_add_f32_e32 v60, v60, v61
	global_store_dwordx2 v[78:79], v[58:59], off offset:2560
	v_add_f32_e32 v62, v62, v60
	global_load_dwordx4 v[22:25], v[72:73], off offset:-3072 nt
	s_waitcnt vmcnt(13)
	v_mul_f32_e32 v60, v49, v49
	v_mul_f32_e32 v61, v51, v51
	v_fmac_f32_e32 v60, v48, v48
	v_fmac_f32_e32 v61, v50, v50
	v_cvt_pk_bf16_f32 v56, v48, v49
	v_cvt_pk_bf16_f32 v57, v50, v51
	v_add_f32_e32 v60, v60, v61
	global_store_dwordx2 v[78:79], v[56:57], off offset:3072
	v_add_f32_e32 v62, v62, v60
	global_load_dwordx4 v[48:51], v[72:73], off offset:-2048 nt
	s_waitcnt vmcnt(14)
	v_mul_f32_e32 v60, v53, v53
	v_mul_f32_e32 v61, v55, v55
	v_fmac_f32_e32 v60, v52, v52
	v_fmac_f32_e32 v61, v54, v54
	v_cvt_pk_bf16_f32 v58, v52, v53
	v_cvt_pk_bf16_f32 v59, v54, v55
	v_add_f32_e32 v60, v60, v61
	global_store_dwordx2 v[78:79], v[58:59], off offset:3584
	v_add_f32_e32 v62, v62, v60
	global_load_dwordx4 v[52:55], v[72:73], off offset:-1024 nt
	s_waitcnt vmcnt(14)
; __device__ __forceinline__ unsigned cvt_pk_bf16(float lo, float hi) { unsigned r; asm volatile("v_cvt_pk_bf16_f32 %0, %1, %2" : "=v"(r) : "v"(lo), "v"(hi)); return r; }
; __device__ __forceinline__ void row_to_bf16_ss(const float* xrow, bf16_t* orow, float* ssp, int lane) {
;     ...
;     for (int j = 0; j < 16; ++j) { const f32x4 v = xr[64 * j]; s += (v[0] * v[0] + v[1] * v[1]) + (v[2] * v[2] + v[3] * v[3]);
;         u32x2 w; w.x = cvt_pk_bf16(v[0], v[1]); w.y = cvt_pk_bf16(v[2], v[3]); o8[64 * j] = w; }
;     s = wave_sum(s); if (lane == 0) *ssp = s;
; }
	v_mul_f32_e32 v60, v3, v3
	v_mul_f32_e32 v61, v5, v5
	v_fmac_f32_e32 v60, v2, v2
	v_fmac_f32_e32 v61, v4, v4
	v_cvt_pk_bf16_f32 v56, v2, v3
	v_cvt_pk_bf16_f32 v57, v4, v5
	v_add_f32_e32 v60, v60, v61
	global_store_dwordx2 v[74:75], v[56:57], off
	v_add_f32_e32 v62, v62, v60
	s_waitcnt vmcnt(13)
	v_mul_f32_e32 v60, v7, v7
	v_mul_f32_e32 v61, v9, v9
	v_fmac_f32_e32 v60, v6, v6
	v_fmac_f32_e32 v61, v8, v8
	v_cvt_pk_bf16_f32 v58, v6, v7
	v_cvt_pk_bf16_f32 v59, v8, v9
	v_add_f32_e32 v60, v60, v61
	global_store_dwordx2 v[74:75], v[58:59], off offset:512
	v_add_f32_e32 v62, v62, v60
	s_waitcnt vmcnt(12)
	v_mul_f32_e32 v60, v11, v11
	v_mul_f32_e32 v61, v13, v13
	v_fmac_f32_e32 v60, v10, v10
	v_fmac_f32_e32 v61, v12, v12
	v_cvt_pk_bf16_f32 v56, v10, v11
	v_cvt_pk_bf16_f32 v57, v12, v13
	v_add_f32_e32 v60, v60, v61
	global_store_dwordx2 v[74:75], v[56:57], off offset:1024
	v_add_f32_e32 v62, v62, v60
	s_waitcnt vmcnt(11)
	v_mul_f32_e32 v60, v15, v15
	v_mul_f32_e32 v61, v17, v17
	v_fmac_f32_e32 v60, v14, v14
	v_fmac_f32_e32 v61, v16, v16
	v_cvt_pk_bf16_f32 v58, v14, v15
	v_cvt_pk_bf16_f32 v59, v16, v17
	v_add_f32_e32 v60, v60, v61
	global_store_dwordx2 v[74:75], v[58:59], off offset:1536
	v_add_f32_e32 v62, v62, v60
	s_waitcnt vmcnt(10)
	v_mul_f32_e32 v60, v19, v19
	v_mul_f32_e32 v61, v21, v21
	v_fmac_f32_e32 v60, v18, v18
	v_fmac_f32_e32 v61, v20, v20
	v_cvt_pk_bf16_f32 v56, v18, v19
	v_cvt_pk_bf16_f32 v57, v20, v21
	v_add_f32_e32 v60, v60, v61
	global_store_dwordx2 v[74:75], v[56:57], off offset:2048
	v_add_f32_e32 v62, v62, v60
	s_waitcnt vmcnt(9)
	v_mul_f32_e32 v60, v23, v23
	v_mul_f32_e32 v61, v25, v25
	v_fmac_f32_e32 v60, v22, v22
	v_fmac_f32_e32 v61, v24, v24
	v_cvt_pk_bf16_f32 v58, v22, v23
	v_cvt_pk_bf16_f32 v59, v24, v25
	v_add_f32_e32 v60, v60, v61
	global_store_dwordx2 v[74:75], v[58:59], off offset:2560
	v_add_f32_e32 v62, v62, v60
	s_waitcnt vmcnt(8)
	v_mul_f32_e32 v60, v49, v49
	v_mul_f32_e32 v61, v51, v51
	v_fmac_f32_e32 v60, v48, v48
	v_fmac_f32_e32 v61, v50, v50
	v_cvt_pk_bf16_f32 v56, v48, v49
	v_cvt_pk_bf16_f32 v57, v50, v51
	v_add_f32_e32 v60, v60, v61
	global_store_dwordx2 v[74:75], v[56:57], off offset:3072
	v_add_f32_e32 v62, v62, v60
	s_waitcnt vmcnt(7)
	v_mul_f32_e32 v60, v53, v53
	v_mul_f32_e32 v61, v55, v55
	v_fmac_f32_e32 v60, v52, v52
	v_fmac_f32_e32 v61, v54, v54
	v_cvt_pk_bf16_f32 v58, v52, v53
	v_cvt_pk_bf16_f32 v59, v54, v55
	v_add_f32_e32 v60, v60, v61
	global_store_dwordx2 v[74:75], v[58:59], off offset:3584
	v_add_f32_e32 v62, v62, v60
	v_mov_b32_e32 v2, v62
	v_cmp_lt_i32_e32 vcc, v42, v41
	v_cndmask_b32_e32 v66, v40, v42, vcc
	v_lshlrev_b32_e32 v66, 2, v66
	ds_bpermute_b32 v3, v66, v2
	v_cmp_lt_i32_e32 vcc, v43, v41
	s_waitcnt lgkmcnt(0)
	v_add_f32_e32 v2, v2, v3
	v_cndmask_b32_e32 v8, v40, v43, vcc
	v_lshlrev_b32_e32 v8, 2, v8
	ds_bpermute_b32 v3, v8, v2
	v_cmp_lt_i32_e32 vcc, v44, v41
	s_waitcnt lgkmcnt(0)
	v_add_f32_e32 v2, v2, v3
	v_cndmask_b32_e32 v8, v40, v44, vcc
	v_lshlrev_b32_e32 v8, 2, v8
	ds_bpermute_b32 v3, v8, v2
	v_cmp_lt_i32_e32 vcc, v45, v41
	s_waitcnt lgkmcnt(0)
	v_add_f32_e32 v2, v2, v3
	v_cndmask_b32_e32 v8, v40, v45, vcc
	v_lshlrev_b32_e32 v8, 2, v8
	ds_bpermute_b32 v3, v8, v2
	v_cmp_lt_i32_e32 vcc, v46, v41
	s_waitcnt lgkmcnt(0)
	v_add_f32_e32 v2, v2, v3
	v_cndmask_b32_e32 v8, v40, v46, vcc
	v_lshlrev_b32_e32 v8, 2, v8
	ds_bpermute_b32 v3, v8, v2
	v_cmp_lt_i32_e32 vcc, v47, v41
	s_waitcnt lgkmcnt(0)
	v_add_f32_e32 v2, v2, v3
	v_cndmask_b32_e32 v8, v40, v47, vcc
	v_lshlrev_b32_e32 v3, 2, v8
	ds_bpermute_b32 v3, v3, v2
	s_and_saveexec_b64 s[4:5], s[0:1]
	s_cbranch_execz .LBB0_51
	s_lshl_b64 s[6:7], s[26:27], 2
	v_readlane_b32 s2, v250, 44
	s_add_u32 s6, s2, s6
	v_readlane_b32 s2, v250, 45
	s_addc_u32 s7, s2, s7
	s_waitcnt lgkmcnt(0)
	v_add_f32_e32 v2, v2, v3
	global_store_dword v67, v2, s[6:7]

; __device__ __forceinline__ unsigned cvt_pk_bf16(float lo, float hi) { unsigned r; asm volatile("v_cvt_pk_bf16_f32 %0, %1, %2" : "=v"(r) : "v"(lo), "v"(hi)); return r; }
; __device__ __forceinline__ void row_to_bf16_ss(const float* xrow, bf16_t* orow, float* ssp, int lane) {
;     const f32x4* xr = (const f32x4*)xrow + lane; u32x2* o8 = (u32x2*)orow + lane; float s = 0.f;
; #pragma unroll
;     for (int j = 0; j < 16; ++j) { const f32x4 v = xr[64 * j]; s += (v[0] * v[0] + v[1] * v[1]) + (v[2] * v[2] + v[3] * v[3]);
;         u32x2 w; w.x = cvt_pk_bf16(v[0], v[1]); w.y = cvt_pk_bf16(v[2], v[3]); o8[64 * j] = w; }
; __device__ __forceinline__ void p0_prologue(const Args& a, LAS unsigned char* lds, int vcu, int G, int tid, int wave, int lane) {
;     ...
;         if (m < MP) row_to_bf16_ss(a.in[I_XP] + (size_t)m * DM, (bf16_t*)(ws + WS_XB) + (size_t)m * DM, ss0 + m, lane);
.LBB0_53:
	s_andn2_b64 vcc, exec, s[4:5]
	s_cbranch_vccnz .LBB0_42
	v_lshl_add_u64 v[78:79], s[90:91], 0, v[36:37]
	s_mov_b64 s[4:5], 0x2b200000
	s_waitcnt lgkmcnt(0)
	v_lshl_add_u64 v[78:79], v[78:79], 0, s[4:5]
	s_mov_b64 s[4:5], 0x2000
	v_lshl_add_u64 v[70:71], v[34:35], 0, s[4:5]
	v_lshl_add_u64 v[72:73], v[70:71], 0, s[4:5]
	s_mov_b64 s[4:5], 0x1000
	v_lshl_add_u64 v[74:75], v[78:79], 0, s[4:5]
	v_mov_b32_e32 v62, 0
	global_load_dwordx4 v[2:5], v[34:35], off nt
	global_load_dwordx4 v[6:9], v[34:35], off offset:1024 nt
	global_load_dwordx4 v[10:13], v[34:35], off offset:2048 nt
	global_load_dwordx4 v[14:17], v[34:35], off offset:3072 nt
	global_load_dwordx4 v[18:21], v[70:71], off offset:-4096 nt
	global_load_dwordx4 v[22:25], v[70:71], off offset:-3072 nt
	global_load_dwordx4 v[48:51], v[70:71], off offset:-2048 nt
	global_load_dwordx4 v[52:55], v[70:71], off offset:-1024 nt
	s_waitcnt vmcnt(7)
	v_mul_f32_e32 v60, v3, v3
	v_mul_f32_e32 v61, v5, v5
	v_fmac_f32_e32 v60, v2, v2
	v_fmac_f32_e32 v61, v4, v4
	v_cvt_pk_bf16_f32 v56, v2, v3
	v_cvt_pk_bf16_f32 v57, v4, v5
	v_add_f32_e32 v60, v60, v61
	global_store_dwordx2 v[78:79], v[56:57], off
	v_add_f32_e32 v62, v62, v60
	global_load_dwordx4 v[2:5], v[70:71], off nt
	s_waitcnt vmcnt(8)
	v_mul_f32_e32 v60, v7, v7
	v_mul_f32_e32 v61, v9, v9
	v_fmac_f32_e32 v60, v6, v6
	v_fmac_f32_e32 v61, v8, v8
	v_cvt_pk_bf16_f32 v58, v6, v7
	v_cvt_pk_bf16_f32 v59, v8, v9
	v_add_f32_e32 v60, v60, v61
	global_store_dwordx2 v[78:79], v[58:59], off offset:512
	v_add_f32_e32 v62, v62, v60
	global_load_dwordx4 v[6:9], v[70:71], off offset:1024 nt
	s_waitcnt vmcnt(9)
	v_mul_f32_e32 v60, v11, v11
	v_mul_f32_e32 v61, v13, v13
	v_fmac_f32_e32 v60, v10, v10
	v_fmac_f32_e32 v61, v12, v12
	v_cvt_pk_bf16_f32 v56, v10, v11
	v_cvt_pk_bf16_f32 v57, v12, v13
	v_add_f32_e32 v60, v60, v61
	global_store_dwordx2 v[78:79], v[56:57], off offset:1024
	v_add_f32_e32 v62, v62, v60
	global_load_dwordx4 v[10:13], v[70:71], off offset:2048 nt
	s_waitcnt vmcnt(10)
	v_mul_f32_e32 v60, v15, v15
	v_mul_f32_e32 v61, v17, v17
	v_fmac_f32_e32 v60, v14, v14
	v_fmac_f32_e32 v61, v16, v16
	v_cvt_pk_bf16_f32 v58, v14, v15
	v_cvt_pk_bf16_f32 v59, v16, v17
	v_add_f32_e32 v60, v60, v61
	global_store_dwordx2 v[78:79], v[58:59], off offset:1536
	v_add_f32_e32 v62, v62, v60
	global_load_dwordx4 v[14:17], v[70:71], off offset:3072 nt
	s_waitcnt vmcnt(11)
	v_mul_f32_e32 v60, v19, v19
	v_mul_f32_e32 v61, v21, v21
	v_fmac_f32_e32 v60, v18, v18
	v_fmac_f32_e32 v61, v20, v20
	v_cvt_pk_bf16_f32 v56, v18, v19
	v_cvt_pk_bf16_f32 v57, v20, v21
	v_add_f32_e32 v60, v60, v61
	global_store_dwordx2 v[78:79], v[56:57], off offset:2048
	v_add_f32_e32 v62, v62, v60
	global_load_dwordx4 v[18:21], v[72:73], off offset:-4096 nt
	s_waitcnt vmcnt(12)
	v_mul_f32_e32 v60, v23, v23
	v_mul_f32_e32 v61, v25, v25
	v_fmac_f32_e32 v60, v22, v22
	v_fmac_f32_e32 v61, v24, v24
	v_cvt_pk_bf16_f32 v58, v22, v23
	v_cvt_pk_bf16_f32 v59, v24, v25
	v_add_f32_e32 v60, v60, v61
	global_store_dwordx2 v[78:79], v[58:59], off offset:2560
	v_add_f32_e32 v62, v62, v60
	global_load_dwordx4 v[22:25], v[72:73], off offset:-3072 nt
	s_waitcnt vmcnt(13)
	v_mul_f32_e32 v60, v49, v49
	v_mul_f32_e32 v61, v51, v51
	v_fmac_f32_e32 v60, v48, v48
	v_fmac_f32_e32 v61, v50, v50
	v_cvt_pk_bf16_f32 v56, v48, v49
	v_cvt_pk_bf16_f32 v57, v50, v51
	v_add_f32_e32 v60, v60, v61
	global_store_dwordx2 v[78:79], v[56:57], off offset:3072
	v_add_f32_e32 v62, v62, v60
	global_load_dwordx4 v[48:51], v[72:73], off offset:-2048 nt
	s_waitcnt vmcnt(14)
	v_mul_f32_e32 v60, v53, v53
	v_mul_f32_e32 v61, v55, v55
	v_fmac_f32_e32 v60, v52, v52
	v_fmac_f32_e32 v61, v54, v54
	v_cvt_pk_bf16_f32 v58, v52, v53
	v_cvt_pk_bf16_f32 v59, v54, v55
	v_add_f32_e32 v60, v60, v61
	global_store_dwordx2 v[78:79], v[58:59], off offset:3584
	v_add_f32_e32 v62, v62, v60
	global_load_dwordx4 v[52:55], v[72:73], off offset:-1024 nt
	s_waitcnt vmcnt(14)
; __device__ __forceinline__ unsigned cvt_pk_bf16(float lo, float hi) { unsigned r; asm volatile("v_cvt_pk_bf16_f32 %0, %1, %2" : "=v"(r) : "v"(lo), "v"(hi)); return r; }
; __device__ __forceinline__ void row_to_bf16_ss(const float* xrow, bf16_t* orow, float* ssp, int lane) {
;     ...
;     for (int j = 0; j < 16; ++j) { const f32x4 v = xr[64 * j]; s += (v[0] * v[0] + v[1] * v[1]) + (v[2] * v[2] + v[3] * v[3]);
;         u32x2 w; w.x = cvt_pk_bf16(v[0], v[1]); w.y = cvt_pk_bf16(v[2], v[3]); o8[64 * j] = w; }
;     s = wave_sum(s); if (lane == 0) *ssp = s;
; }
	v_mul_f32_e32 v60, v3, v3
	v_mul_f32_e32 v61, v5, v5
	v_fmac_f32_e32 v60, v2, v2
	v_fmac_f32_e32 v61, v4, v4
	v_cvt_pk_bf16_f32 v56, v2, v3
	v_cvt_pk_bf16_f32 v57, v4, v5
	v_add_f32_e32 v60, v60, v61
	global_store_dwordx2 v[74:75], v[56:57], off
	v_add_f32_e32 v62, v62, v60
	s_waitcnt vmcnt(13)
	v_mul_f32_e32 v60, v7, v7
	v_mul_f32_e32 v61, v9, v9
	v_fmac_f32_e32 v60, v6, v6
	v_fmac_f32_e32 v61, v8, v8
	v_cvt_pk_bf16_f32 v58, v6, v7
	v_cvt_pk_bf16_f32 v59, v8, v9
	v_add_f32_e32 v60, v60, v61
	global_store_dwordx2 v[74:75], v[58:59], off offset:512
	v_add_f32_e32 v62, v62, v60
	s_waitcnt vmcnt(12)
	v_mul_f32_e32 v60, v11, v11
	v_mul_f32_e32 v61, v13, v13
	v_fmac_f32_e32 v60, v10, v10
	v_fmac_f32_e32 v61, v12, v12
	v_cvt_pk_bf16_f32 v56, v10, v11
	v_cvt_pk_bf16_f32 v57, v12, v13
	v_add_f32_e32 v60, v60, v61
	global_store_dwordx2 v[74:75], v[56:57], off offset:1024
	v_add_f32_e32 v62, v62, v60
	s_waitcnt vmcnt(11)
	v_mul_f32_e32 v60, v15, v15
	v_mul_f32_e32 v61, v17, v17
	v_fmac_f32_e32 v60, v14, v14
	v_fmac_f32_e32 v61, v16, v16
	v_cvt_pk_bf16_f32 v58, v14, v15
	v_cvt_pk_bf16_f32 v59, v16, v17
	v_add_f32_e32 v60, v60, v61
	global_store_dwordx2 v[74:75], v[58:59], off offset:1536
	v_add_f32_e32 v62, v62, v60
	s_waitcnt vmcnt(10)
	v_mul_f32_e32 v60, v19, v19
	v_mul_f32_e32 v61, v21, v21
	v_fmac_f32_e32 v60, v18, v18
	v_fmac_f32_e32 v61, v20, v20
	v_cvt_pk_bf16_f32 v56, v18, v19
	v_cvt_pk_bf16_f32 v57, v20, v21
	v_add_f32_e32 v60, v60, v61
	global_store_dwordx2 v[74:75], v[56:57], off offset:2048
	v_add_f32_e32 v62, v62, v60
	s_waitcnt vmcnt(9)
	v_mul_f32_e32 v60, v23, v23
	v_mul_f32_e32 v61, v25, v25
	v_fmac_f32_e32 v60, v22, v22
	v_fmac_f32_e32 v61, v24, v24
	v_cvt_pk_bf16_f32 v58, v22, v23
	v_cvt_pk_bf16_f32 v59, v24, v25
	v_add_f32_e32 v60, v60, v61
	global_store_dwordx2 v[74:75], v[58:59], off offset:2560
	v_add_f32_e32 v62, v62, v60
	s_waitcnt vmcnt(8)
	v_mul_f32_e32 v60, v49, v49
	v_mul_f32_e32 v61, v51, v51
	v_fmac_f32_e32 v60, v48, v48
	v_fmac_f32_e32 v61, v50, v50
	v_cvt_pk_bf16_f32 v56, v48, v49
	v_cvt_pk_bf16_f32 v57, v50, v51
	v_add_f32_e32 v60, v60, v61
	global_store_dwordx2 v[74:75], v[56:57], off offset:3072
	v_add_f32_e32 v62, v62, v60
	s_waitcnt vmcnt(7)
	v_mul_f32_e32 v60, v53, v53
	v_mul_f32_e32 v61, v55, v55
	v_fmac_f32_e32 v60, v52, v52
	v_fmac_f32_e32 v61, v54, v54
	v_cvt_pk_bf16_f32 v58, v52, v53
	v_cvt_pk_bf16_f32 v59, v54, v55
	v_add_f32_e32 v60, v60, v61
	global_store_dwordx2 v[74:75], v[58:59], off offset:3584
	v_add_f32_e32 v62, v62, v60
	v_mov_b32_e32 v2, v62
	v_cmp_lt_i32_e32 vcc, v42, v41
	v_cndmask_b32_e32 v66, v40, v42, vcc
	v_lshlrev_b32_e32 v66, 2, v66
	ds_bpermute_b32 v3, v66, v2
	v_cmp_lt_i32_e32 vcc, v43, v41
	s_waitcnt lgkmcnt(0)
	v_add_f32_e32 v2, v2, v3
	v_cndmask_b32_e32 v8, v40, v43, vcc
	v_lshlrev_b32_e32 v8, 2, v8
	ds_bpermute_b32 v3, v8, v2
	v_cmp_lt_i32_e32 vcc, v44, v41
	s_waitcnt lgkmcnt(0)
	v_add_f32_e32 v2, v2, v3
	v_cndmask_b32_e32 v8, v40, v44, vcc
	v_lshlrev_b32_e32 v8, 2, v8
	ds_bpermute_b32 v3, v8, v2
	v_cmp_lt_i32_e32 vcc, v45, v41
	s_waitcnt lgkmcnt(0)
	v_add_f32_e32 v2, v2, v3
	v_cndmask_b32_e32 v8, v40, v45, vcc
	v_lshlrev_b32_e32 v8, 2, v8
	ds_bpermute_b32 v3, v8, v2
	v_cmp_lt_i32_e32 vcc, v46, v41
	s_waitcnt lgkmcnt(0)
	v_add_f32_e32 v2, v2, v3
	v_cndmask_b32_e32 v8, v40, v46, vcc
	v_lshlrev_b32_e32 v8, 2, v8
	ds_bpermute_b32 v3, v8, v2
	v_cmp_lt_i32_e32 vcc, v47, v41
	s_waitcnt lgkmcnt(0)
	v_add_f32_e32 v2, v2, v3
	v_cndmask_b32_e32 v8, v40, v47, vcc
	v_lshlrev_b32_e32 v3, 2, v8
	ds_bpermute_b32 v3, v3, v2
	s_and_saveexec_b64 s[4:5], s[0:1]
	s_cbranch_execz .LBB0_41
	s_add_u32 s6, s90, s3
	s_addc_u32 s7, s91, s38
	s_waitcnt lgkmcnt(0)
	v_add_f32_e32 v2, v2, v3
	global_store_dword v67, v2, s[6:7]
	s_branch .LBB0_41
